# S5 step C epilogue: hoisted 16 uu + 2 dsk loads to epilogue top, waits become vmcnt(15) (no store-ack serialization)
# speedup vs baseline: 1.0106x; 1.0044x over previous
.LBB0_494:
	v_add_u32_e32 v132, s21, v147
	v_lshlrev_b64 v[96:97], 5, v[132:133]
	v_lshl_add_u64 v[100:101], v[160:161], 0, v[96:97]
	global_load_dwordx4 v[216:219], v[156:157], off
	global_load_dwordx4 v[220:223], v[158:159], off offset:32
	global_load_dwordx2 v[184:185], v[100:101], off
	global_load_dwordx2 v[186:187], v[100:101], off offset:16
	global_load_dwordx2 v[188:189], v[100:101], off offset:32
	global_load_dwordx2 v[190:191], v[100:101], off offset:48
	global_load_dwordx2 v[192:193], v[100:101], off offset:64
	global_load_dwordx2 v[194:195], v[100:101], off offset:80
	global_load_dwordx2 v[196:197], v[100:101], off offset:96
	global_load_dwordx2 v[198:199], v[100:101], off offset:112
	global_load_dwordx2 v[200:201], v[100:101], off offset:128
	global_load_dwordx2 v[202:203], v[100:101], off offset:144
	global_load_dwordx2 v[204:205], v[100:101], off offset:160
	global_load_dwordx2 v[206:207], v[100:101], off offset:176
	global_load_dwordx2 v[208:209], v[100:101], off offset:192
	global_load_dwordx2 v[210:211], v[100:101], off offset:208
	global_load_dwordx2 v[212:213], v[100:101], off offset:224
	global_load_dwordx2 v[214:215], v[100:101], off offset:240
	v_mov_b32_e32 v105, v133
	v_add_u32_e32 v104, s44, v132
	v_lshlrev_b64 v[104:105], 12, v[104:105]
	s_add_i32 s20, s20, 1
	s_cmp_eq_u32 s20, 4
	v_add_u32_e32 v182, 8, v182
	s_waitcnt vmcnt(15)
	v_lshlrev_b32_e32 v106, 16, v184
	v_and_b32_e32 v107, 0xffff0000, v184
	v_lshlrev_b32_e32 v102, 16, v185
	v_and_b32_e32 v103, 0xffff0000, v185
	v_pk_fma_f32 v[48:49], v[216:217], v[106:107], v[48:49]
	v_pk_fma_f32 v[50:51], v[218:219], v[102:103], v[50:51]
	v_mul_f32_e32 v96, 0x3d372713, v48
	v_mul_f32_e32 v97, 0x3d372713, v49
	v_mul_f32_e32 v98, 0x3d372713, v50
	v_mul_f32_e32 v99, 0x3d372713, v51
	v_mul_f32_e32 v96, v48, v96
	v_mul_f32_e32 v97, v49, v97
	v_mul_f32_e32 v98, v50, v98
	v_mul_f32_e32 v99, v51, v99
	v_fma_f32 v96, v48, v96, v48
	v_fma_f32 v97, v49, v97, v49
	v_fma_f32 v98, v50, v98, v50
	v_fma_f32 v99, v51, v99, v51
	v_mul_f32_e32 v96, 0x3f4c422a, v96
	v_mul_f32_e32 v97, 0x3f4c422a, v97
	v_mul_f32_e32 v98, 0x3f4c422a, v98
	v_mul_f32_e32 v99, 0x3f4c422a, v99
	v_mul_f32_e32 v96, -2.0, v96
	v_mul_f32_e32 v97, -2.0, v97
	v_mul_f32_e32 v98, -2.0, v98
	v_mul_f32_e32 v99, -2.0, v99
	v_mul_f32_e32 v96, 0x3fb8aa3b, v96
	v_mul_f32_e32 v97, 0x3fb8aa3b, v97
	v_mul_f32_e32 v98, 0x3fb8aa3b, v98
	v_mul_f32_e32 v99, 0x3fb8aa3b, v99
	v_exp_f32_e32 v96, v96
	v_exp_f32_e32 v97, v97
	v_exp_f32_e32 v98, v98
	v_exp_f32_e32 v99, v99
	v_add_f32_e32 v96, 1.0, v96
	v_add_f32_e32 v97, 1.0, v97
	v_add_f32_e32 v98, 1.0, v98
	v_add_f32_e32 v99, 1.0, v99
	v_rcp_f32_e32 v96, v96
	v_rcp_f32_e32 v97, v97
	v_rcp_f32_e32 v98, v98
	v_rcp_f32_e32 v99, v99
	v_lshl_add_u64 v[102:103], s[10:11], 0, v[104:105]
	v_pk_mul_f32 v[48:49], v[48:49], v[96:97]
	v_lshl_add_u64 v[104:105], v[102:103], 0, v[164:165]
	v_pk_mul_f32 v[50:51], v[50:51], v[98:99]
	v_cvt_pk_bf16_f32 v48, v48, v49
	v_cvt_pk_bf16_f32 v49, v50, v51
	global_store_dwordx2 v[104:105], v[48:49], off
	s_nop 0
	v_mov_b32_e32 v99, v133
	v_or_b32_e32 v98, 1, v132
	v_lshlrev_b64 v[100:101], 5, v[98:99]
	s_waitcnt vmcnt(15)
	v_lshlrev_b32_e32 v104, 16, v186
	v_and_b32_e32 v105, 0xffff0000, v186
	v_lshlrev_b32_e32 v96, 16, v187
	v_and_b32_e32 v97, 0xffff0000, v187
	v_pk_fma_f32 v[48:49], v[220:221], v[104:105], v[52:53]
	v_pk_fma_f32 v[50:51], v[222:223], v[96:97], v[54:55]
	v_mul_f32_e32 v52, 0x3d372713, v48
	v_mul_f32_e32 v53, 0x3d372713, v49
	v_mul_f32_e32 v54, 0x3d372713, v50
	v_mul_f32_e32 v55, 0x3d372713, v51
	v_mul_f32_e32 v52, v48, v52
	v_mul_f32_e32 v53, v49, v53
	v_mul_f32_e32 v54, v50, v54
	v_mul_f32_e32 v55, v51, v55
	v_fma_f32 v52, v48, v52, v48
	v_fma_f32 v53, v49, v53, v49
	v_fma_f32 v54, v50, v54, v50
	v_fma_f32 v55, v51, v55, v51
	v_mul_f32_e32 v52, 0x3f4c422a, v52
	v_mul_f32_e32 v53, 0x3f4c422a, v53
	v_mul_f32_e32 v54, 0x3f4c422a, v54
	v_mul_f32_e32 v55, 0x3f4c422a, v55
	v_mul_f32_e32 v52, -2.0, v52
	v_mul_f32_e32 v53, -2.0, v53
	v_mul_f32_e32 v54, -2.0, v54
	v_mul_f32_e32 v55, -2.0, v55
	v_mul_f32_e32 v52, 0x3fb8aa3b, v52
	v_mul_f32_e32 v53, 0x3fb8aa3b, v53
	v_mul_f32_e32 v54, 0x3fb8aa3b, v54
	v_mul_f32_e32 v55, 0x3fb8aa3b, v55
	v_exp_f32_e32 v52, v52
	v_exp_f32_e32 v53, v53
	v_exp_f32_e32 v54, v54
	v_exp_f32_e32 v55, v55
	v_add_f32_e32 v52, 1.0, v52
	v_add_f32_e32 v53, 1.0, v53
	v_add_f32_e32 v54, 1.0, v54
	v_add_f32_e32 v55, 1.0, v55
	v_rcp_f32_e32 v52, v52
	v_rcp_f32_e32 v53, v53
	v_rcp_f32_e32 v54, v54
	v_rcp_f32_e32 v55, v55
	v_lshl_add_u64 v[96:97], v[160:161], 0, v[100:101]
	v_pk_mul_f32 v[48:49], v[48:49], v[52:53]
	v_lshl_add_u64 v[100:101], v[102:103], 0, v[166:167]
	v_pk_mul_f32 v[50:51], v[50:51], v[54:55]
	v_cvt_pk_bf16_f32 v48, v48, v49
	v_cvt_pk_bf16_f32 v49, v50, v51
	global_store_dwordx2 v[100:101], v[48:49], off offset:16
	s_nop 0
	v_add_u32_e32 v54, s44, v98
	v_mov_b32_e32 v55, v133
	v_lshlrev_b64 v[54:55], 12, v[54:55]
	v_lshl_add_u64 v[54:55], s[10:11], 0, v[54:55]
	s_waitcnt vmcnt(15)
	v_lshlrev_b32_e32 v98, 16, v188
	v_and_b32_e32 v99, 0xffff0000, v188
	v_lshlrev_b32_e32 v52, 16, v189
	v_and_b32_e32 v53, 0xffff0000, v189
	v_pk_fma_f32 v[48:49], v[216:217], v[98:99], v[56:57]
	v_pk_fma_f32 v[50:51], v[218:219], v[52:53], v[58:59]
	v_mul_f32_e32 v52, 0x3d372713, v48
	v_mul_f32_e32 v53, 0x3d372713, v49
	v_mul_f32_e32 v56, 0x3d372713, v50
	v_mul_f32_e32 v57, 0x3d372713, v51
	v_mul_f32_e32 v52, v48, v52
	v_mul_f32_e32 v53, v49, v53
	v_mul_f32_e32 v56, v50, v56
	v_mul_f32_e32 v57, v51, v57
	v_fma_f32 v52, v48, v52, v48
	v_fma_f32 v53, v49, v53, v49
	v_fma_f32 v56, v50, v56, v50
	v_fma_f32 v57, v51, v57, v51
	v_mul_f32_e32 v52, 0x3f4c422a, v52
	v_mul_f32_e32 v53, 0x3f4c422a, v53
	v_mul_f32_e32 v56, 0x3f4c422a, v56
	v_mul_f32_e32 v57, 0x3f4c422a, v57
	v_mul_f32_e32 v52, -2.0, v52
	v_mul_f32_e32 v53, -2.0, v53
	v_mul_f32_e32 v56, -2.0, v56
	v_mul_f32_e32 v57, -2.0, v57
	v_mul_f32_e32 v52, 0x3fb8aa3b, v52
	v_mul_f32_e32 v53, 0x3fb8aa3b, v53
	v_mul_f32_e32 v56, 0x3fb8aa3b, v56
	v_mul_f32_e32 v57, 0x3fb8aa3b, v57
	v_exp_f32_e32 v52, v52
	v_exp_f32_e32 v53, v53
	v_exp_f32_e32 v56, v56
	v_exp_f32_e32 v57, v57
	v_add_f32_e32 v52, 1.0, v52
	v_add_f32_e32 v53, 1.0, v53
	v_add_f32_e32 v56, 1.0, v56
	v_add_f32_e32 v57, 1.0, v57
	v_rcp_f32_e32 v52, v52
	v_rcp_f32_e32 v53, v53
	v_rcp_f32_e32 v56, v56
	v_rcp_f32_e32 v57, v57
	v_lshl_add_u64 v[58:59], v[54:55], 0, v[164:165]
	v_pk_mul_f32 v[48:49], v[48:49], v[52:53]
	v_lshl_add_u64 v[54:55], v[54:55], 0, v[166:167]
	v_pk_mul_f32 v[50:51], v[50:51], v[56:57]
	v_cvt_pk_bf16_f32 v48, v48, v49
	v_cvt_pk_bf16_f32 v49, v50, v51
	global_store_dwordx2 v[58:59], v[48:49], off
	s_nop 0
	v_mov_b32_e32 v57, v133
	v_or_b32_e32 v56, 2, v132
	v_lshlrev_b64 v[58:59], 5, v[56:57]
	v_lshl_add_u64 v[58:59], v[160:161], 0, v[58:59]
	s_waitcnt vmcnt(15)
	v_lshlrev_b32_e32 v96, 16, v190
	v_and_b32_e32 v97, 0xffff0000, v190
	v_lshlrev_b32_e32 v52, 16, v191
	v_and_b32_e32 v53, 0xffff0000, v191
	v_pk_fma_f32 v[48:49], v[220:221], v[96:97], v[60:61]
	v_pk_fma_f32 v[50:51], v[222:223], v[52:53], v[62:63]
	v_mul_f32_e32 v52, 0x3d372713, v48
	v_mul_f32_e32 v53, 0x3d372713, v49
	v_mul_f32_e32 v57, 0x3d372713, v50
	v_mul_f32_e32 v60, 0x3d372713, v51
	v_mul_f32_e32 v52, v48, v52
	v_mul_f32_e32 v53, v49, v53
	v_mul_f32_e32 v57, v50, v57
	v_mul_f32_e32 v60, v51, v60
	v_fma_f32 v52, v48, v52, v48
	v_fma_f32 v53, v49, v53, v49
	v_fma_f32 v57, v50, v57, v50
	v_fma_f32 v60, v51, v60, v51
	v_mul_f32_e32 v52, 0x3f4c422a, v52
	v_mul_f32_e32 v53, 0x3f4c422a, v53
	v_mul_f32_e32 v57, 0x3f4c422a, v57
	v_mul_f32_e32 v60, 0x3f4c422a, v60
	v_mul_f32_e32 v52, -2.0, v52
	v_mul_f32_e32 v53, -2.0, v53
	v_mul_f32_e32 v57, -2.0, v57
	v_mul_f32_e32 v60, -2.0, v60
	v_mul_f32_e32 v52, 0x3fb8aa3b, v52
	v_mul_f32_e32 v53, 0x3fb8aa3b, v53
	v_mul_f32_e32 v57, 0x3fb8aa3b, v57
	v_mul_f32_e32 v60, 0x3fb8aa3b, v60
	v_exp_f32_e32 v52, v52
	v_exp_f32_e32 v53, v53
	v_exp_f32_e32 v57, v57
	v_exp_f32_e32 v60, v60
	v_add_f32_e32 v52, 1.0, v52
	v_add_f32_e32 v53, 1.0, v53
	v_add_f32_e32 v57, 1.0, v57
	v_add_f32_e32 v61, 1.0, v60
	v_rcp_f32_e32 v52, v52
	v_rcp_f32_e32 v53, v53
	v_rcp_f32_e32 v60, v57
	v_rcp_f32_e32 v61, v61
	v_pk_mul_f32 v[48:49], v[48:49], v[52:53]
	s_nop 0
	v_cvt_pk_bf16_f32 v48, v48, v49
	v_pk_mul_f32 v[50:51], v[50:51], v[60:61]
	s_nop 0
	v_cvt_pk_bf16_f32 v49, v50, v51
	global_store_dwordx2 v[54:55], v[48:49], off offset:16
	s_nop 0
	v_add_u32_e32 v54, s44, v56
	v_mov_b32_e32 v55, v133
	v_lshlrev_b64 v[54:55], 12, v[54:55]
	s_waitcnt vmcnt(15)
	v_lshlrev_b32_e32 v56, 16, v192
	v_and_b32_e32 v57, 0xffff0000, v192
	v_lshlrev_b32_e32 v52, 16, v193
	v_and_b32_e32 v53, 0xffff0000, v193
	v_pk_fma_f32 v[32:33], v[216:217], v[56:57], v[32:33]
	v_pk_fma_f32 v[34:35], v[218:219], v[52:53], v[34:35]
	v_mul_f32_e32 v48, 0x3d372713, v32
	v_mul_f32_e32 v49, 0x3d372713, v33
	v_mul_f32_e32 v50, 0x3d372713, v34
	v_mul_f32_e32 v51, 0x3d372713, v35
	v_mul_f32_e32 v48, v32, v48
	v_mul_f32_e32 v49, v33, v49
	v_mul_f32_e32 v50, v34, v50
	v_mul_f32_e32 v51, v35, v51
	v_fma_f32 v48, v32, v48, v32
	v_fma_f32 v49, v33, v49, v33
	v_fma_f32 v50, v34, v50, v34
	v_fma_f32 v51, v35, v51, v35
	v_mul_f32_e32 v48, 0x3f4c422a, v48
	v_mul_f32_e32 v49, 0x3f4c422a, v49
	v_mul_f32_e32 v50, 0x3f4c422a, v50
	v_mul_f32_e32 v51, 0x3f4c422a, v51
	v_mul_f32_e32 v48, -2.0, v48
	v_mul_f32_e32 v49, -2.0, v49
	v_mul_f32_e32 v50, -2.0, v50
	v_mul_f32_e32 v51, -2.0, v51
	v_mul_f32_e32 v48, 0x3fb8aa3b, v48
	v_mul_f32_e32 v49, 0x3fb8aa3b, v49
	v_mul_f32_e32 v50, 0x3fb8aa3b, v50
	v_mul_f32_e32 v51, 0x3fb8aa3b, v51
	v_exp_f32_e32 v48, v48
	v_exp_f32_e32 v49, v49
	v_exp_f32_e32 v50, v50
	v_exp_f32_e32 v51, v51
	v_add_f32_e32 v48, 1.0, v48
	v_add_f32_e32 v49, 1.0, v49
	v_add_f32_e32 v50, 1.0, v50
	v_add_f32_e32 v51, 1.0, v51
	v_rcp_f32_e32 v48, v48
	v_rcp_f32_e32 v49, v49
	v_rcp_f32_e32 v50, v50
	v_rcp_f32_e32 v51, v51
	v_lshl_add_u64 v[52:53], s[10:11], 0, v[54:55]
	v_pk_mul_f32 v[32:33], v[32:33], v[48:49]
	v_lshl_add_u64 v[54:55], v[52:53], 0, v[164:165]
	v_pk_mul_f32 v[34:35], v[34:35], v[50:51]
	v_cvt_pk_bf16_f32 v32, v32, v33
	v_cvt_pk_bf16_f32 v33, v34, v35
	global_store_dwordx2 v[54:55], v[32:33], off
	s_nop 0
	v_mov_b32_e32 v51, v133
	v_or_b32_e32 v50, 3, v132
	v_lshlrev_b64 v[54:55], 5, v[50:51]
	v_lshl_add_u64 v[52:53], v[52:53], 0, v[166:167]
	s_waitcnt vmcnt(15)
	v_lshlrev_b32_e32 v56, 16, v194
	v_and_b32_e32 v57, 0xffff0000, v194
	v_lshlrev_b32_e32 v48, 16, v195
	v_and_b32_e32 v49, 0xffff0000, v195
	v_pk_fma_f32 v[32:33], v[220:221], v[56:57], v[36:37]
	v_pk_fma_f32 v[34:35], v[222:223], v[48:49], v[38:39]
	v_mul_f32_e32 v36, 0x3d372713, v32
	v_mul_f32_e32 v37, 0x3d372713, v33
	v_mul_f32_e32 v38, 0x3d372713, v34
	v_mul_f32_e32 v39, 0x3d372713, v35
	v_mul_f32_e32 v36, v32, v36
	v_mul_f32_e32 v37, v33, v37
	v_mul_f32_e32 v38, v34, v38
	v_mul_f32_e32 v39, v35, v39
	v_fma_f32 v36, v32, v36, v32
	v_fma_f32 v37, v33, v37, v33
	v_fma_f32 v38, v34, v38, v34
	v_fma_f32 v39, v35, v39, v35
	v_mul_f32_e32 v36, 0x3f4c422a, v36
	v_mul_f32_e32 v37, 0x3f4c422a, v37
	v_mul_f32_e32 v38, 0x3f4c422a, v38
	v_mul_f32_e32 v39, 0x3f4c422a, v39
	v_mul_f32_e32 v36, -2.0, v36
	v_mul_f32_e32 v37, -2.0, v37
	v_mul_f32_e32 v38, -2.0, v38
	v_mul_f32_e32 v39, -2.0, v39
	v_mul_f32_e32 v36, 0x3fb8aa3b, v36
	v_mul_f32_e32 v37, 0x3fb8aa3b, v37
	v_mul_f32_e32 v38, 0x3fb8aa3b, v38
	v_mul_f32_e32 v39, 0x3fb8aa3b, v39
	v_exp_f32_e32 v36, v36
	v_exp_f32_e32 v37, v37
	v_exp_f32_e32 v38, v38
	v_exp_f32_e32 v39, v39
	v_add_f32_e32 v36, 1.0, v36
	v_add_f32_e32 v37, 1.0, v37
	v_add_f32_e32 v38, 1.0, v38
	v_add_f32_e32 v39, 1.0, v39
	v_rcp_f32_e32 v36, v36
	v_rcp_f32_e32 v37, v37
	v_rcp_f32_e32 v38, v38
	v_rcp_f32_e32 v39, v39
	v_lshl_add_u64 v[48:49], v[160:161], 0, v[54:55]
	v_pk_mul_f32 v[32:33], v[32:33], v[36:37]
	v_pk_mul_f32 v[34:35], v[34:35], v[38:39]
	v_cvt_pk_bf16_f32 v32, v32, v33
	v_cvt_pk_bf16_f32 v33, v34, v35
	global_store_dwordx2 v[52:53], v[32:33], off offset:16
	s_nop 0
	v_add_u32_e32 v38, s44, v50
	v_mov_b32_e32 v39, v133
	v_lshlrev_b64 v[38:39], 12, v[38:39]
	v_lshl_add_u64 v[38:39], s[10:11], 0, v[38:39]
	s_waitcnt vmcnt(15)
	v_lshlrev_b32_e32 v50, 16, v196
	v_and_b32_e32 v51, 0xffff0000, v196
	v_lshlrev_b32_e32 v36, 16, v197
	v_and_b32_e32 v37, 0xffff0000, v197
	v_pk_fma_f32 v[32:33], v[216:217], v[50:51], v[40:41]
	v_pk_fma_f32 v[34:35], v[218:219], v[36:37], v[42:43]
	v_mul_f32_e32 v36, 0x3d372713, v32
	v_mul_f32_e32 v37, 0x3d372713, v33
	v_mul_f32_e32 v40, 0x3d372713, v34
	v_mul_f32_e32 v41, 0x3d372713, v35
	v_mul_f32_e32 v36, v32, v36
	v_mul_f32_e32 v37, v33, v37
	v_mul_f32_e32 v40, v34, v40
	v_mul_f32_e32 v41, v35, v41
	v_fma_f32 v36, v32, v36, v32
	v_fma_f32 v37, v33, v37, v33
	v_fma_f32 v40, v34, v40, v34
	v_fma_f32 v41, v35, v41, v35
	v_mul_f32_e32 v36, 0x3f4c422a, v36
	v_mul_f32_e32 v37, 0x3f4c422a, v37
	v_mul_f32_e32 v40, 0x3f4c422a, v40
	v_mul_f32_e32 v41, 0x3f4c422a, v41
	v_mul_f32_e32 v36, -2.0, v36
	v_mul_f32_e32 v37, -2.0, v37
	v_mul_f32_e32 v40, -2.0, v40
	v_mul_f32_e32 v41, -2.0, v41
	v_mul_f32_e32 v36, 0x3fb8aa3b, v36
	v_mul_f32_e32 v37, 0x3fb8aa3b, v37
	v_mul_f32_e32 v40, 0x3fb8aa3b, v40
	v_mul_f32_e32 v41, 0x3fb8aa3b, v41
	v_exp_f32_e32 v36, v36
	v_exp_f32_e32 v37, v37
	v_exp_f32_e32 v40, v40
	v_exp_f32_e32 v41, v41
	v_add_f32_e32 v36, 1.0, v36
	v_add_f32_e32 v37, 1.0, v37
	v_add_f32_e32 v40, 1.0, v40
	v_add_f32_e32 v41, 1.0, v41
	v_rcp_f32_e32 v36, v36
	v_rcp_f32_e32 v37, v37
	v_rcp_f32_e32 v40, v40
	v_rcp_f32_e32 v41, v41
	v_lshl_add_u64 v[42:43], v[38:39], 0, v[164:165]
	v_pk_mul_f32 v[32:33], v[32:33], v[36:37]
	v_lshl_add_u64 v[38:39], v[38:39], 0, v[166:167]
	v_pk_mul_f32 v[34:35], v[34:35], v[40:41]
	v_cvt_pk_bf16_f32 v32, v32, v33
	v_cvt_pk_bf16_f32 v33, v34, v35
	global_store_dwordx2 v[42:43], v[32:33], off
	s_nop 0
	v_mov_b32_e32 v41, v133
	v_or_b32_e32 v40, 4, v132
	v_lshlrev_b64 v[42:43], 5, v[40:41]
	v_lshl_add_u64 v[42:43], v[160:161], 0, v[42:43]
	s_waitcnt vmcnt(15)
	v_lshlrev_b32_e32 v48, 16, v198
	v_and_b32_e32 v49, 0xffff0000, v198
	v_lshlrev_b32_e32 v36, 16, v199
	v_and_b32_e32 v37, 0xffff0000, v199
	v_pk_fma_f32 v[32:33], v[220:221], v[48:49], v[44:45]
	v_pk_fma_f32 v[34:35], v[222:223], v[36:37], v[46:47]
	v_mul_f32_e32 v36, 0x3d372713, v32
	v_mul_f32_e32 v37, 0x3d372713, v33
	v_mul_f32_e32 v41, 0x3d372713, v34
	v_mul_f32_e32 v44, 0x3d372713, v35
	v_mul_f32_e32 v36, v32, v36
	v_mul_f32_e32 v37, v33, v37
	v_mul_f32_e32 v41, v34, v41
	v_mul_f32_e32 v44, v35, v44
	v_fma_f32 v36, v32, v36, v32
	v_fma_f32 v37, v33, v37, v33
	v_fma_f32 v41, v34, v41, v34
	v_fma_f32 v44, v35, v44, v35
	v_mul_f32_e32 v36, 0x3f4c422a, v36
	v_mul_f32_e32 v37, 0x3f4c422a, v37
	v_mul_f32_e32 v41, 0x3f4c422a, v41
	v_mul_f32_e32 v44, 0x3f4c422a, v44
	v_mul_f32_e32 v36, -2.0, v36
	v_mul_f32_e32 v37, -2.0, v37
	v_mul_f32_e32 v41, -2.0, v41
	v_mul_f32_e32 v44, -2.0, v44
	v_mul_f32_e32 v36, 0x3fb8aa3b, v36
	v_mul_f32_e32 v37, 0x3fb8aa3b, v37
	v_mul_f32_e32 v41, 0x3fb8aa3b, v41
	v_mul_f32_e32 v44, 0x3fb8aa3b, v44
	v_exp_f32_e32 v36, v36
	v_exp_f32_e32 v37, v37
	v_exp_f32_e32 v41, v41
	v_exp_f32_e32 v44, v44
	v_add_f32_e32 v36, 1.0, v36
	v_add_f32_e32 v37, 1.0, v37
	v_add_f32_e32 v41, 1.0, v41
	v_add_f32_e32 v45, 1.0, v44
	v_rcp_f32_e32 v36, v36
	v_rcp_f32_e32 v37, v37
	v_rcp_f32_e32 v44, v41
	v_rcp_f32_e32 v45, v45
	v_pk_mul_f32 v[32:33], v[32:33], v[36:37]
	s_nop 0
	v_cvt_pk_bf16_f32 v32, v32, v33
	v_pk_mul_f32 v[34:35], v[34:35], v[44:45]
	s_nop 0
	v_cvt_pk_bf16_f32 v33, v34, v35
	global_store_dwordx2 v[38:39], v[32:33], off offset:16
	s_nop 0
	v_add_u32_e32 v38, s44, v40
	v_mov_b32_e32 v39, v133
	v_lshlrev_b64 v[38:39], 12, v[38:39]
	s_waitcnt vmcnt(15)
	v_lshlrev_b32_e32 v40, 16, v200
	v_and_b32_e32 v41, 0xffff0000, v200
	v_lshlrev_b32_e32 v36, 16, v201
	v_and_b32_e32 v37, 0xffff0000, v201
	v_pk_fma_f32 v[16:17], v[216:217], v[40:41], v[16:17]
	v_pk_fma_f32 v[18:19], v[218:219], v[36:37], v[18:19]
	v_mul_f32_e32 v32, 0x3d372713, v16
	v_mul_f32_e32 v33, 0x3d372713, v17
	v_mul_f32_e32 v34, 0x3d372713, v18
	v_mul_f32_e32 v35, 0x3d372713, v19
	v_mul_f32_e32 v32, v16, v32
	v_mul_f32_e32 v33, v17, v33
	v_mul_f32_e32 v34, v18, v34
	v_mul_f32_e32 v35, v19, v35
	v_fma_f32 v32, v16, v32, v16
	v_fma_f32 v33, v17, v33, v17
	v_fma_f32 v34, v18, v34, v18
	v_fma_f32 v35, v19, v35, v19
	v_mul_f32_e32 v32, 0x3f4c422a, v32
	v_mul_f32_e32 v33, 0x3f4c422a, v33
	v_mul_f32_e32 v34, 0x3f4c422a, v34
	v_mul_f32_e32 v35, 0x3f4c422a, v35
	v_mul_f32_e32 v32, -2.0, v32
	v_mul_f32_e32 v33, -2.0, v33
	v_mul_f32_e32 v34, -2.0, v34
	v_mul_f32_e32 v35, -2.0, v35
	v_mul_f32_e32 v32, 0x3fb8aa3b, v32
	v_mul_f32_e32 v33, 0x3fb8aa3b, v33
	v_mul_f32_e32 v34, 0x3fb8aa3b, v34
	v_mul_f32_e32 v35, 0x3fb8aa3b, v35
	v_exp_f32_e32 v32, v32
	v_exp_f32_e32 v33, v33
	v_exp_f32_e32 v34, v34
	v_exp_f32_e32 v35, v35
	v_add_f32_e32 v32, 1.0, v32
	v_add_f32_e32 v33, 1.0, v33
	v_add_f32_e32 v34, 1.0, v34
	v_add_f32_e32 v35, 1.0, v35
	v_rcp_f32_e32 v32, v32
	v_rcp_f32_e32 v33, v33
	v_rcp_f32_e32 v34, v34
	v_rcp_f32_e32 v35, v35
	v_lshl_add_u64 v[36:37], s[10:11], 0, v[38:39]
	v_pk_mul_f32 v[16:17], v[16:17], v[32:33]
	v_lshl_add_u64 v[38:39], v[36:37], 0, v[164:165]
	v_pk_mul_f32 v[18:19], v[18:19], v[34:35]
	v_cvt_pk_bf16_f32 v16, v16, v17
	v_cvt_pk_bf16_f32 v17, v18, v19
	global_store_dwordx2 v[38:39], v[16:17], off
	s_nop 0
	v_mov_b32_e32 v35, v133
	v_or_b32_e32 v34, 5, v132
	v_lshlrev_b64 v[38:39], 5, v[34:35]
	v_lshl_add_u64 v[36:37], v[36:37], 0, v[166:167]
	s_waitcnt vmcnt(15)
	v_lshlrev_b32_e32 v40, 16, v202
	v_and_b32_e32 v41, 0xffff0000, v202
	v_lshlrev_b32_e32 v32, 16, v203
	v_and_b32_e32 v33, 0xffff0000, v203
	v_pk_fma_f32 v[16:17], v[220:221], v[40:41], v[20:21]
	v_pk_fma_f32 v[18:19], v[222:223], v[32:33], v[22:23]
	v_mul_f32_e32 v20, 0x3d372713, v16
	v_mul_f32_e32 v21, 0x3d372713, v17
	v_mul_f32_e32 v22, 0x3d372713, v18
	v_mul_f32_e32 v23, 0x3d372713, v19
	v_mul_f32_e32 v20, v16, v20
	v_mul_f32_e32 v21, v17, v21
	v_mul_f32_e32 v22, v18, v22
	v_mul_f32_e32 v23, v19, v23
	v_fma_f32 v20, v16, v20, v16
	v_fma_f32 v21, v17, v21, v17
	v_fma_f32 v22, v18, v22, v18
	v_fma_f32 v23, v19, v23, v19
	v_mul_f32_e32 v20, 0x3f4c422a, v20
	v_mul_f32_e32 v21, 0x3f4c422a, v21
	v_mul_f32_e32 v22, 0x3f4c422a, v22
	v_mul_f32_e32 v23, 0x3f4c422a, v23
	v_mul_f32_e32 v20, -2.0, v20
	v_mul_f32_e32 v21, -2.0, v21
	v_mul_f32_e32 v22, -2.0, v22
	v_mul_f32_e32 v23, -2.0, v23
	v_mul_f32_e32 v20, 0x3fb8aa3b, v20
	v_mul_f32_e32 v21, 0x3fb8aa3b, v21
	v_mul_f32_e32 v22, 0x3fb8aa3b, v22
	v_mul_f32_e32 v23, 0x3fb8aa3b, v23
	v_exp_f32_e32 v20, v20
	v_exp_f32_e32 v21, v21
	v_exp_f32_e32 v22, v22
	v_exp_f32_e32 v23, v23
	v_add_f32_e32 v20, 1.0, v20
	v_add_f32_e32 v21, 1.0, v21
	v_add_f32_e32 v22, 1.0, v22
	v_add_f32_e32 v23, 1.0, v23
	v_rcp_f32_e32 v20, v20
	v_rcp_f32_e32 v21, v21
	v_rcp_f32_e32 v22, v22
	v_rcp_f32_e32 v23, v23
	v_lshl_add_u64 v[32:33], v[160:161], 0, v[38:39]
	v_pk_mul_f32 v[16:17], v[16:17], v[20:21]
	v_pk_mul_f32 v[18:19], v[18:19], v[22:23]
	v_cvt_pk_bf16_f32 v16, v16, v17
	v_cvt_pk_bf16_f32 v17, v18, v19
	global_store_dwordx2 v[36:37], v[16:17], off offset:16
	s_nop 0
	v_add_u32_e32 v22, s44, v34
	v_mov_b32_e32 v23, v133
	v_lshlrev_b64 v[22:23], 12, v[22:23]
	v_lshl_add_u64 v[22:23], s[10:11], 0, v[22:23]
	s_waitcnt vmcnt(15)
	v_lshlrev_b32_e32 v34, 16, v204
	v_and_b32_e32 v35, 0xffff0000, v204
	v_lshlrev_b32_e32 v20, 16, v205
	v_and_b32_e32 v21, 0xffff0000, v205
	v_pk_fma_f32 v[16:17], v[216:217], v[34:35], v[24:25]
	v_pk_fma_f32 v[18:19], v[218:219], v[20:21], v[26:27]
	v_mul_f32_e32 v20, 0x3d372713, v16
	v_mul_f32_e32 v21, 0x3d372713, v17
	v_mul_f32_e32 v24, 0x3d372713, v18
	v_mul_f32_e32 v25, 0x3d372713, v19
	v_mul_f32_e32 v20, v16, v20
	v_mul_f32_e32 v21, v17, v21
	v_mul_f32_e32 v24, v18, v24
	v_mul_f32_e32 v25, v19, v25
	v_fma_f32 v20, v16, v20, v16
	v_fma_f32 v21, v17, v21, v17
	v_fma_f32 v24, v18, v24, v18
	v_fma_f32 v25, v19, v25, v19
	v_mul_f32_e32 v20, 0x3f4c422a, v20
	v_mul_f32_e32 v21, 0x3f4c422a, v21
	v_mul_f32_e32 v24, 0x3f4c422a, v24
	v_mul_f32_e32 v25, 0x3f4c422a, v25
	v_mul_f32_e32 v20, -2.0, v20
	v_mul_f32_e32 v21, -2.0, v21
	v_mul_f32_e32 v24, -2.0, v24
	v_mul_f32_e32 v25, -2.0, v25
	v_mul_f32_e32 v20, 0x3fb8aa3b, v20
	v_mul_f32_e32 v21, 0x3fb8aa3b, v21
	v_mul_f32_e32 v24, 0x3fb8aa3b, v24
	v_mul_f32_e32 v25, 0x3fb8aa3b, v25
	v_exp_f32_e32 v20, v20
	v_exp_f32_e32 v21, v21
	v_exp_f32_e32 v24, v24
	v_exp_f32_e32 v25, v25
	v_add_f32_e32 v20, 1.0, v20
	v_add_f32_e32 v21, 1.0, v21
	v_add_f32_e32 v24, 1.0, v24
	v_add_f32_e32 v25, 1.0, v25
	v_rcp_f32_e32 v20, v20
	v_rcp_f32_e32 v21, v21
	v_rcp_f32_e32 v24, v24
	v_rcp_f32_e32 v25, v25
	v_lshl_add_u64 v[26:27], v[22:23], 0, v[164:165]
	v_pk_mul_f32 v[16:17], v[16:17], v[20:21]
	v_lshl_add_u64 v[22:23], v[22:23], 0, v[166:167]
	v_pk_mul_f32 v[18:19], v[18:19], v[24:25]
	v_cvt_pk_bf16_f32 v16, v16, v17
	v_cvt_pk_bf16_f32 v17, v18, v19
	global_store_dwordx2 v[26:27], v[16:17], off
	s_nop 0
	v_mov_b32_e32 v25, v133
	v_or_b32_e32 v24, 6, v132
	v_lshlrev_b64 v[26:27], 5, v[24:25]
	v_lshl_add_u64 v[26:27], v[160:161], 0, v[26:27]
	v_or_b32_e32 v132, 7, v132
	s_waitcnt vmcnt(15)
	v_lshlrev_b32_e32 v32, 16, v206
	v_and_b32_e32 v33, 0xffff0000, v206
	v_lshlrev_b32_e32 v20, 16, v207
	v_and_b32_e32 v21, 0xffff0000, v207
	v_pk_fma_f32 v[16:17], v[220:221], v[32:33], v[28:29]
	v_pk_fma_f32 v[18:19], v[222:223], v[20:21], v[30:31]
	v_mul_f32_e32 v20, 0x3d372713, v16
	v_mul_f32_e32 v21, 0x3d372713, v17
	v_mul_f32_e32 v25, 0x3d372713, v18
	v_mul_f32_e32 v28, 0x3d372713, v19
	v_mul_f32_e32 v20, v16, v20
	v_mul_f32_e32 v21, v17, v21
	v_mul_f32_e32 v25, v18, v25
	v_mul_f32_e32 v28, v19, v28
	v_fma_f32 v20, v16, v20, v16
	v_fma_f32 v21, v17, v21, v17
	v_fma_f32 v25, v18, v25, v18
	v_fma_f32 v28, v19, v28, v19
	v_mul_f32_e32 v20, 0x3f4c422a, v20
	v_mul_f32_e32 v21, 0x3f4c422a, v21
	v_mul_f32_e32 v25, 0x3f4c422a, v25
	v_mul_f32_e32 v28, 0x3f4c422a, v28
	v_mul_f32_e32 v20, -2.0, v20
	v_mul_f32_e32 v21, -2.0, v21
	v_mul_f32_e32 v25, -2.0, v25
	v_mul_f32_e32 v28, -2.0, v28
	v_mul_f32_e32 v20, 0x3fb8aa3b, v20
	v_mul_f32_e32 v21, 0x3fb8aa3b, v21
	v_mul_f32_e32 v25, 0x3fb8aa3b, v25
	v_mul_f32_e32 v28, 0x3fb8aa3b, v28
	v_exp_f32_e32 v20, v20
	v_exp_f32_e32 v21, v21
	v_exp_f32_e32 v25, v25
	v_exp_f32_e32 v28, v28
	v_add_f32_e32 v20, 1.0, v20
	v_add_f32_e32 v21, 1.0, v21
	v_add_f32_e32 v25, 1.0, v25
	v_add_f32_e32 v29, 1.0, v28
	v_rcp_f32_e32 v20, v20
	v_rcp_f32_e32 v21, v21
	v_rcp_f32_e32 v28, v25
	v_rcp_f32_e32 v29, v29
	v_pk_mul_f32 v[16:17], v[16:17], v[20:21]
	s_nop 0
	v_cvt_pk_bf16_f32 v16, v16, v17
	v_pk_mul_f32 v[18:19], v[18:19], v[28:29]
	s_nop 0
	v_cvt_pk_bf16_f32 v17, v18, v19
	global_store_dwordx2 v[22:23], v[16:17], off offset:16
	s_nop 0
	v_add_u32_e32 v22, s44, v24
	v_mov_b32_e32 v23, v133
	v_lshlrev_b64 v[22:23], 12, v[22:23]
	s_waitcnt vmcnt(15)
	v_lshlrev_b32_e32 v24, 16, v208
	v_and_b32_e32 v25, 0xffff0000, v208
	v_lshlrev_b32_e32 v20, 16, v209
	v_and_b32_e32 v21, 0xffff0000, v209
	v_pk_fma_f32 v[0:1], v[216:217], v[24:25], v[0:1]
	v_pk_fma_f32 v[2:3], v[218:219], v[20:21], v[2:3]
	v_mul_f32_e32 v16, 0x3d372713, v0
	v_mul_f32_e32 v17, 0x3d372713, v1
	v_mul_f32_e32 v18, 0x3d372713, v2
	v_mul_f32_e32 v19, 0x3d372713, v3
	v_mul_f32_e32 v16, v0, v16
	v_mul_f32_e32 v17, v1, v17
	v_mul_f32_e32 v18, v2, v18
	v_mul_f32_e32 v19, v3, v19
	v_fma_f32 v16, v0, v16, v0
	v_fma_f32 v17, v1, v17, v1
	v_fma_f32 v18, v2, v18, v2
	v_fma_f32 v19, v3, v19, v3
	v_mul_f32_e32 v16, 0x3f4c422a, v16
	v_mul_f32_e32 v17, 0x3f4c422a, v17
	v_mul_f32_e32 v18, 0x3f4c422a, v18
	v_mul_f32_e32 v19, 0x3f4c422a, v19
	v_mul_f32_e32 v16, -2.0, v16
	v_mul_f32_e32 v17, -2.0, v17
	v_mul_f32_e32 v18, -2.0, v18
	v_mul_f32_e32 v19, -2.0, v19
	v_mul_f32_e32 v16, 0x3fb8aa3b, v16
	v_mul_f32_e32 v17, 0x3fb8aa3b, v17
	v_mul_f32_e32 v18, 0x3fb8aa3b, v18
	v_mul_f32_e32 v19, 0x3fb8aa3b, v19
	v_exp_f32_e32 v16, v16
	v_exp_f32_e32 v17, v17
	v_exp_f32_e32 v18, v18
	v_exp_f32_e32 v19, v19
	v_add_f32_e32 v16, 1.0, v16
	v_add_f32_e32 v17, 1.0, v17
	v_add_f32_e32 v18, 1.0, v18
	v_add_f32_e32 v19, 1.0, v19
	v_rcp_f32_e32 v16, v16
	v_rcp_f32_e32 v17, v17
	v_rcp_f32_e32 v18, v18
	v_rcp_f32_e32 v19, v19
	v_lshl_add_u64 v[20:21], s[10:11], 0, v[22:23]
	v_pk_mul_f32 v[0:1], v[0:1], v[16:17]
	v_lshl_add_u64 v[22:23], v[20:21], 0, v[164:165]
	v_pk_mul_f32 v[2:3], v[2:3], v[18:19]
	v_cvt_pk_bf16_f32 v0, v0, v1
	v_cvt_pk_bf16_f32 v1, v2, v3
	global_store_dwordx2 v[22:23], v[0:1], off
	s_nop 0
	v_lshlrev_b64 v[18:19], 5, v[132:133]
	v_add_u32_e32 v132, s44, v132
	s_waitcnt vmcnt(15)
	v_lshlrev_b32_e32 v22, 16, v210
	v_and_b32_e32 v23, 0xffff0000, v210
	v_lshlrev_b32_e32 v16, 16, v211
	v_and_b32_e32 v17, 0xffff0000, v211
	v_pk_fma_f32 v[0:1], v[220:221], v[22:23], v[4:5]
	v_pk_fma_f32 v[2:3], v[222:223], v[16:17], v[6:7]
	v_mul_f32_e32 v4, 0x3d372713, v0
	v_mul_f32_e32 v5, 0x3d372713, v1
	v_mul_f32_e32 v6, 0x3d372713, v2
	v_mul_f32_e32 v7, 0x3d372713, v3
	v_mul_f32_e32 v4, v0, v4
	v_mul_f32_e32 v5, v1, v5
	v_mul_f32_e32 v6, v2, v6
	v_mul_f32_e32 v7, v3, v7
	v_fma_f32 v4, v0, v4, v0
	v_fma_f32 v5, v1, v5, v1
	v_fma_f32 v6, v2, v6, v2
	v_fma_f32 v7, v3, v7, v3
	v_mul_f32_e32 v4, 0x3f4c422a, v4
	v_mul_f32_e32 v5, 0x3f4c422a, v5
	v_mul_f32_e32 v6, 0x3f4c422a, v6
	v_mul_f32_e32 v7, 0x3f4c422a, v7
	v_mul_f32_e32 v4, -2.0, v4
	v_mul_f32_e32 v5, -2.0, v5
	v_mul_f32_e32 v6, -2.0, v6
	v_mul_f32_e32 v7, -2.0, v7
	v_mul_f32_e32 v4, 0x3fb8aa3b, v4
	v_mul_f32_e32 v5, 0x3fb8aa3b, v5
	v_mul_f32_e32 v6, 0x3fb8aa3b, v6
	v_mul_f32_e32 v7, 0x3fb8aa3b, v7
	v_exp_f32_e32 v4, v4
	v_exp_f32_e32 v5, v5
	v_exp_f32_e32 v6, v6
	v_exp_f32_e32 v7, v7
	v_add_f32_e32 v4, 1.0, v4
	v_add_f32_e32 v5, 1.0, v5
	v_add_f32_e32 v6, 1.0, v6
	v_add_f32_e32 v7, 1.0, v7
	v_rcp_f32_e32 v4, v4
	v_rcp_f32_e32 v5, v5
	v_rcp_f32_e32 v6, v6
	v_rcp_f32_e32 v7, v7
	v_lshl_add_u64 v[16:17], v[160:161], 0, v[18:19]
	v_pk_mul_f32 v[0:1], v[0:1], v[4:5]
	v_lshl_add_u64 v[18:19], v[20:21], 0, v[166:167]
	v_pk_mul_f32 v[2:3], v[2:3], v[6:7]
	v_cvt_pk_bf16_f32 v0, v0, v1
	v_cvt_pk_bf16_f32 v1, v2, v3
	global_store_dwordx2 v[18:19], v[0:1], off offset:16
	s_nop 0
	v_lshlrev_b64 v[6:7], 12, v[132:133]
	v_lshl_add_u64 v[6:7], s[10:11], 0, v[6:7]
	s_waitcnt vmcnt(15)
	v_lshlrev_b32_e32 v18, 16, v212
	v_and_b32_e32 v19, 0xffff0000, v212
	v_lshlrev_b32_e32 v4, 16, v213
	v_and_b32_e32 v5, 0xffff0000, v213
	v_pk_fma_f32 v[0:1], v[216:217], v[18:19], v[8:9]
	v_pk_fma_f32 v[2:3], v[218:219], v[4:5], v[10:11]
	v_mul_f32_e32 v4, 0x3d372713, v0
	v_mul_f32_e32 v5, 0x3d372713, v1
	v_mul_f32_e32 v8, 0x3d372713, v2
	v_mul_f32_e32 v9, 0x3d372713, v3
	v_mul_f32_e32 v4, v0, v4
	v_mul_f32_e32 v5, v1, v5
	v_mul_f32_e32 v8, v2, v8
	v_mul_f32_e32 v9, v3, v9
	v_fma_f32 v4, v0, v4, v0
	v_fma_f32 v5, v1, v5, v1
	v_fma_f32 v8, v2, v8, v2
	v_fma_f32 v9, v3, v9, v3
	v_mul_f32_e32 v4, 0x3f4c422a, v4
	v_mul_f32_e32 v5, 0x3f4c422a, v5
	v_mul_f32_e32 v8, 0x3f4c422a, v8
	v_mul_f32_e32 v9, 0x3f4c422a, v9
	v_mul_f32_e32 v4, -2.0, v4
	v_mul_f32_e32 v5, -2.0, v5
	v_mul_f32_e32 v8, -2.0, v8
	v_mul_f32_e32 v9, -2.0, v9
	v_mul_f32_e32 v4, 0x3fb8aa3b, v4
	v_mul_f32_e32 v5, 0x3fb8aa3b, v5
	v_mul_f32_e32 v8, 0x3fb8aa3b, v8
	v_mul_f32_e32 v9, 0x3fb8aa3b, v9
	v_exp_f32_e32 v4, v4
	v_exp_f32_e32 v5, v5
	v_exp_f32_e32 v8, v8
	v_exp_f32_e32 v9, v9
	v_add_f32_e32 v4, 1.0, v4
	v_add_f32_e32 v5, 1.0, v5
	v_add_f32_e32 v8, 1.0, v8
	v_add_f32_e32 v9, 1.0, v9
	v_rcp_f32_e32 v4, v4
	v_rcp_f32_e32 v5, v5
	v_rcp_f32_e32 v8, v8
	v_rcp_f32_e32 v9, v9
	v_lshl_add_u64 v[10:11], v[6:7], 0, v[164:165]
	v_pk_mul_f32 v[0:1], v[0:1], v[4:5]
	v_lshl_add_u64 v[6:7], v[6:7], 0, v[166:167]
	v_pk_mul_f32 v[2:3], v[2:3], v[8:9]
	v_cvt_pk_bf16_f32 v0, v0, v1
	v_cvt_pk_bf16_f32 v1, v2, v3
	global_store_dwordx2 v[10:11], v[0:1], off
	s_nop 0
	s_waitcnt vmcnt(15)
	v_lshlrev_b32_e32 v8, 16, v214
	v_and_b32_e32 v9, 0xffff0000, v214
	v_lshlrev_b32_e32 v4, 16, v215
	v_and_b32_e32 v5, 0xffff0000, v215
	v_pk_fma_f32 v[0:1], v[220:221], v[8:9], v[12:13]
	v_pk_fma_f32 v[2:3], v[222:223], v[4:5], v[14:15]
	v_mul_f32_e32 v4, 0x3d372713, v0
	v_mul_f32_e32 v5, 0x3d372713, v1
	v_mul_f32_e32 v8, 0x3d372713, v2
	v_mul_f32_e32 v9, 0x3d372713, v3
	v_mul_f32_e32 v4, v0, v4
	v_mul_f32_e32 v5, v1, v5
	v_mul_f32_e32 v8, v2, v8
	v_mul_f32_e32 v9, v3, v9
	v_fma_f32 v4, v0, v4, v0
	v_fma_f32 v5, v1, v5, v1
	v_fma_f32 v8, v2, v8, v2
	v_fma_f32 v9, v3, v9, v3
	v_mul_f32_e32 v4, 0x3f4c422a, v4
	v_mul_f32_e32 v5, 0x3f4c422a, v5
	v_mul_f32_e32 v8, 0x3f4c422a, v8
	v_mul_f32_e32 v9, 0x3f4c422a, v9
	v_mul_f32_e32 v4, -2.0, v4
	v_mul_f32_e32 v5, -2.0, v5
	v_mul_f32_e32 v8, -2.0, v8
	v_mul_f32_e32 v9, -2.0, v9
	v_mul_f32_e32 v4, 0x3fb8aa3b, v4
	v_mul_f32_e32 v5, 0x3fb8aa3b, v5
	v_mul_f32_e32 v8, 0x3fb8aa3b, v8
	v_mul_f32_e32 v9, 0x3fb8aa3b, v9
	v_exp_f32_e32 v4, v4
	v_exp_f32_e32 v5, v5
	v_exp_f32_e32 v8, v8
	v_exp_f32_e32 v9, v9
	v_add_f32_e32 v4, 1.0, v4
	v_add_f32_e32 v5, 1.0, v5
	v_add_f32_e32 v8, 1.0, v8
	v_add_f32_e32 v9, 1.0, v9
	v_rcp_f32_e32 v4, v4
	v_rcp_f32_e32 v5, v5
	v_rcp_f32_e32 v8, v8
	v_rcp_f32_e32 v9, v9
	v_pk_mul_f32 v[0:1], v[0:1], v[4:5]
	s_nop 0
	v_cvt_pk_bf16_f32 v0, v0, v1
	v_pk_mul_f32 v[2:3], v[2:3], v[8:9]
	s_nop 0
	v_cvt_pk_bf16_f32 v1, v2, v3
	global_store_dwordx2 v[6:7], v[0:1], off offset:16
	s_cbranch_scc1 .LBB0_484
